# second conversion loop of each pair (P0 W3A, P8 W1B) walks wave ranks in reverse so the extra item of a non-divisible split lands on different waves
# speedup vs baseline: 1.0171x; 1.0086x over previous
; #define GAS __attribute__((address_space(1)))
; #define LAS __attribute__((address_space(3)))
; template <int MODE>
; __device__ __forceinline__ void p0_transpose_item8(const float* W, int K, int N, unsigned char* WT, float scale, LAS float* scr, int item, int lane) {
;     const int nblk = N / 32, kb = item / nblk, nb = item % nblk, k0 = 128 * kb, n0 = 32 * nb;
;     const GAS float* Wg = (const GAS float*)W;
; #pragma unroll
;     for (int h2 = 0; h2 < 2; ++h2) { float ld[32];
; #pragma unroll
;         for (int i = 0; i < 32; ++i) { const int kk = 2 * (i + 32 * h2) + (lane >> 5); ld[i] = __builtin_nontemporal_load(&Wg[(size_t)(k0 + kk) * N + n0 + (lane & 31)]); }
; template <int JOB>
; __device__ __forceinline__ void conv_job(Frame& F, const Args& A, int rank, int nw) {
;     ...
;     for (int it = rank; it < N; it += nw) {
;         if constexpr (JOB == JOB_W1A) p0_transpose_item8<1>(A.in[I_W1A], D, FF, ws + WS_W13A, S_W13, scr, it, F.lane);
.LBB0_19:
	s_mul_hi_i32 s2, s15, 0x2fa0be83
	s_lshr_b32 s3, s2, 31
	s_ashr_i32 s2, s2, 6
	s_add_i32 s3, s2, s3
	s_mul_i32 s4, s3, 0xffffd500
	s_lshl_b32 s2, s3, 7
	s_mulk_i32 s3, 0xfea8
	s_add_i32 s4, s14, s4
	v_or_b32_e32 v63, s2, v19
	s_add_i32 s16, s15, s3
	s_ashr_i32 s5, s4, 31
	v_or_b32_e32 v68, 2, v63
	v_or_b32_e32 v70, 4, v63
	v_or_b32_e32 v72, 6, v63
	v_or_b32_e32 v74, 8, v63
	v_or_b32_e32 v76, 10, v63
	v_or_b32_e32 v78, 12, v63
	v_or_b32_e32 v80, 14, v63
	v_or_b32_e32 v82, 16, v63
	v_or_b32_e32 v84, 18, v63
	v_or_b32_e32 v86, 20, v63
	v_or_b32_e32 v88, 22, v63
	v_or_b32_e32 v90, 24, v63
	v_or_b32_e32 v92, 26, v63
	v_or_b32_e32 v94, 28, v63
	v_or_b32_e32 v96, 30, v63
	v_or_b32_e32 v98, 32, v63
	v_or_b32_e32 v100, 34, v63
	v_or_b32_e32 v102, 36, v63
	v_or_b32_e32 v104, 38, v63
	v_or_b32_e32 v106, 40, v63
	v_or_b32_e32 v108, 42, v63
	v_or_b32_e32 v110, 44, v63
	v_or_b32_e32 v112, 46, v63
	v_or_b32_e32 v114, 48, v63
	v_or_b32_e32 v116, 50, v63
	v_or_b32_e32 v118, 52, v63
	v_or_b32_e32 v120, 54, v63
	v_or_b32_e32 v122, 56, v63
	v_or_b32_e32 v124, 58, v63
	v_or_b32_e32 v126, 60, v63
	v_or_b32_e32 v128, 62, v63
	s_bfe_u32 s17, s16, 0x2001d
	v_lshl_add_u64 v[64:65], s[4:5], 2, v[22:23]
	v_or_b32_e32 v130, 64, v63
	v_or_b32_e32 v132, 0x42, v63
	v_or_b32_e32 v134, 0x44, v63
	v_or_b32_e32 v136, 0x46, v63
	v_or_b32_e32 v138, 0x48, v63
	v_or_b32_e32 v140, 0x4a, v63
	v_or_b32_e32 v142, 0x4c, v63
	v_or_b32_e32 v144, 0x4e, v63
	v_or_b32_e32 v146, 0x50, v63
	v_or_b32_e32 v148, 0x52, v63
	v_or_b32_e32 v150, 0x54, v63
	v_or_b32_e32 v152, 0x56, v63
	v_or_b32_e32 v154, 0x58, v63
	v_or_b32_e32 v156, 0x5a, v63
	v_or_b32_e32 v158, 0x5c, v63
	v_or_b32_e32 v160, 0x5e, v63
	v_or_b32_e32 v163, 0x60, v63
	v_or_b32_e32 v166, 0x62, v63
	v_or_b32_e32 v168, 0x64, v63
	v_or_b32_e32 v170, 0x66, v63
	v_or_b32_e32 v172, 0x68, v63
	v_or_b32_e32 v174, 0x6a, v63
	v_or_b32_e32 v176, 0x6c, v63
	v_or_b32_e32 v178, 0x6e, v63
	v_or_b32_e32 v180, 0x70, v63
	v_or_b32_e32 v182, 0x72, v63
	v_or_b32_e32 v184, 0x74, v63
	v_or_b32_e32 v186, 0x76, v63
	v_or_b32_e32 v188, 0x78, v63
	v_or_b32_e32 v190, 0x7a, v63
	v_or_b32_e32 v192, 0x7c, v63
	v_or_b32_e32 v194, 0x7e, v63
	s_add_i32 s5, s16, s17
	v_mad_i64_i32 v[66:67], s[16:17], v63, s8, v[64:65]
	v_mad_i64_i32 v[68:69], s[16:17], v68, s8, v[64:65]
	v_mad_i64_i32 v[70:71], s[16:17], v70, s8, v[64:65]
	v_mad_i64_i32 v[72:73], s[16:17], v72, s8, v[64:65]
	v_mad_i64_i32 v[74:75], s[16:17], v74, s8, v[64:65]
	v_mad_i64_i32 v[76:77], s[16:17], v76, s8, v[64:65]
	v_mad_i64_i32 v[78:79], s[16:17], v78, s8, v[64:65]
	v_mad_i64_i32 v[80:81], s[16:17], v80, s8, v[64:65]
	v_mad_i64_i32 v[82:83], s[16:17], v82, s8, v[64:65]
	v_mad_i64_i32 v[84:85], s[16:17], v84, s8, v[64:65]
	v_mad_i64_i32 v[86:87], s[16:17], v86, s8, v[64:65]
	v_mad_i64_i32 v[88:89], s[16:17], v88, s8, v[64:65]
	v_mad_i64_i32 v[90:91], s[16:17], v90, s8, v[64:65]
	v_mad_i64_i32 v[92:93], s[16:17], v92, s8, v[64:65]
	v_mad_i64_i32 v[94:95], s[16:17], v94, s8, v[64:65]
	v_mad_i64_i32 v[96:97], s[16:17], v96, s8, v[64:65]
	v_mad_i64_i32 v[98:99], s[16:17], v98, s8, v[64:65]
	v_mad_i64_i32 v[100:101], s[16:17], v100, s8, v[64:65]
	v_mad_i64_i32 v[102:103], s[16:17], v102, s8, v[64:65]
	v_mad_i64_i32 v[104:105], s[16:17], v104, s8, v[64:65]
	v_mad_i64_i32 v[106:107], s[16:17], v106, s8, v[64:65]
	v_mad_i64_i32 v[108:109], s[16:17], v108, s8, v[64:65]
	v_mad_i64_i32 v[110:111], s[16:17], v110, s8, v[64:65]
	v_mad_i64_i32 v[112:113], s[16:17], v112, s8, v[64:65]
	v_mad_i64_i32 v[114:115], s[16:17], v114, s8, v[64:65]
	v_mad_i64_i32 v[116:117], s[16:17], v116, s8, v[64:65]
	v_mad_i64_i32 v[118:119], s[16:17], v118, s8, v[64:65]
	v_mad_i64_i32 v[120:121], s[16:17], v120, s8, v[64:65]
	v_mad_i64_i32 v[122:123], s[16:17], v122, s8, v[64:65]
	v_mad_i64_i32 v[124:125], s[16:17], v124, s8, v[64:65]
	v_mad_i64_i32 v[126:127], s[16:17], v126, s8, v[64:65]
	v_mad_i64_i32 v[128:129], s[16:17], v128, s8, v[64:65]
	v_mad_i64_i32 v[130:131], s[16:17], v130, s8, v[64:65]
	v_mad_i64_i32 v[132:133], s[16:17], v132, s8, v[64:65]
	v_mad_i64_i32 v[134:135], s[16:17], v134, s8, v[64:65]
	v_mad_i64_i32 v[136:137], s[16:17], v136, s8, v[64:65]
	v_mad_i64_i32 v[138:139], s[16:17], v138, s8, v[64:65]
	v_mad_i64_i32 v[140:141], s[16:17], v140, s8, v[64:65]
	v_mad_i64_i32 v[142:143], s[16:17], v142, s8, v[64:65]
	v_mad_i64_i32 v[144:145], s[16:17], v144, s8, v[64:65]
	v_mad_i64_i32 v[146:147], s[16:17], v146, s8, v[64:65]
	v_mad_i64_i32 v[148:149], s[16:17], v148, s8, v[64:65]
	v_mad_i64_i32 v[150:151], s[16:17], v150, s8, v[64:65]
	v_mad_i64_i32 v[152:153], s[16:17], v152, s8, v[64:65]
	v_mad_i64_i32 v[154:155], s[16:17], v154, s8, v[64:65]
	v_mad_i64_i32 v[156:157], s[16:17], v156, s8, v[64:65]
	v_mad_i64_i32 v[158:159], s[16:17], v158, s8, v[64:65]
	v_mad_i64_i32 v[160:161], s[16:17], v160, s8, v[64:65]
	v_mad_i64_i32 v[164:165], s[16:17], v163, s8, v[64:65]
	v_mad_i64_i32 v[166:167], s[16:17], v166, s8, v[64:65]
	v_mad_i64_i32 v[168:169], s[16:17], v168, s8, v[64:65]
	v_mad_i64_i32 v[170:171], s[16:17], v170, s8, v[64:65]
	v_mad_i64_i32 v[172:173], s[16:17], v172, s8, v[64:65]
	v_mad_i64_i32 v[174:175], s[16:17], v174, s8, v[64:65]
	v_mad_i64_i32 v[176:177], s[16:17], v176, s8, v[64:65]
	v_mad_i64_i32 v[178:179], s[16:17], v178, s8, v[64:65]
	v_mad_i64_i32 v[180:181], s[16:17], v180, s8, v[64:65]
	v_mad_i64_i32 v[182:183], s[16:17], v182, s8, v[64:65]
	v_mad_i64_i32 v[184:185], s[16:17], v184, s8, v[64:65]
	v_mad_i64_i32 v[186:187], s[16:17], v186, s8, v[64:65]
	v_mad_i64_i32 v[188:189], s[16:17], v188, s8, v[64:65]
	v_mad_i64_i32 v[190:191], s[16:17], v190, s8, v[64:65]
	v_mad_i64_i32 v[192:193], s[16:17], v192, s8, v[64:65]
; #define LDS_WAIT() asm volatile("s_waitcnt lgkmcnt(0)" ::: "memory")
; template <int MODE>
; __device__ __forceinline__ void p0_transpose_item8(const float* W, int K, int N, unsigned char* WT, float scale, LAS float* scr, int item, int lane) {
;     ...
;     for (int h2 = 0; h2 < 2; ++h2) { float ld[32];
; #pragma unroll
;         for (int i = 0; i < 32; ++i) { const int kk = 2 * (i + 32 * h2) + (lane >> 5); ld[i] = __builtin_nontemporal_load(&Wg[(size_t)(k0 + kk) * N + n0 + (lane & 31)]); }
; #pragma unroll
;         for (int i = 0; i < 32; ++i) { const int kk = 2 * (i + 32 * h2) + (lane >> 5); scr[kk * 33 + (lane & 31)] = ld[i]; } }
;     LDS_WAIT(); asm volatile("" ::: "memory");
	v_mad_i64_i32 v[64:65], s[16:17], v194, s8, v[64:65]
	global_load_dword v63, v[66:67], off nt
	s_nop 0
	global_load_dword v66, v[68:69], off nt
	global_load_dword v67, v[70:71], off nt
	s_nop 0
	global_load_dword v68, v[72:73], off nt
	global_load_dword v69, v[74:75], off nt
	global_load_dword v70, v[76:77], off nt
	global_load_dword v71, v[78:79], off nt
	s_nop 0
	global_load_dword v72, v[80:81], off nt
	global_load_dword v73, v[82:83], off nt
	global_load_dword v74, v[84:85], off nt
	global_load_dword v75, v[86:87], off nt
	global_load_dword v76, v[88:89], off nt
	global_load_dword v77, v[90:91], off nt
	global_load_dword v78, v[92:93], off nt
	global_load_dword v79, v[94:95], off nt
	global_load_dword v80, v[96:97], off nt
	global_load_dword v81, v[98:99], off nt
	global_load_dword v82, v[100:101], off nt
	global_load_dword v83, v[102:103], off nt
	global_load_dword v84, v[104:105], off nt
	global_load_dword v85, v[106:107], off nt
	global_load_dword v86, v[108:109], off nt
	global_load_dword v87, v[110:111], off nt
	global_load_dword v88, v[112:113], off nt
	global_load_dword v89, v[114:115], off nt
	global_load_dword v90, v[116:117], off nt
	global_load_dword v91, v[118:119], off nt
	global_load_dword v92, v[120:121], off nt
	global_load_dword v93, v[122:123], off nt
	global_load_dword v94, v[124:125], off nt
	global_load_dword v95, v[126:127], off nt
	global_load_dword v96, v[128:129], off nt
	global_load_dword v97, v[130:131], off nt
	global_load_dword v98, v[132:133], off nt
	global_load_dword v99, v[134:135], off nt
	global_load_dword v100, v[136:137], off nt
	global_load_dword v101, v[138:139], off nt
	global_load_dword v102, v[140:141], off nt
	global_load_dword v103, v[142:143], off nt
	global_load_dword v104, v[144:145], off nt
	global_load_dword v105, v[146:147], off nt
	global_load_dword v106, v[148:149], off nt
	global_load_dword v107, v[150:151], off nt
	global_load_dword v108, v[152:153], off nt
	global_load_dword v109, v[154:155], off nt
	global_load_dword v110, v[156:157], off nt
	global_load_dword v111, v[158:159], off nt
	global_load_dword v112, v[160:161], off nt
	global_load_dword v113, v[164:165], off nt
	global_load_dword v114, v[166:167], off nt
	global_load_dword v115, v[168:169], off nt
	global_load_dword v116, v[170:171], off nt
	global_load_dword v117, v[172:173], off nt
	global_load_dword v118, v[174:175], off nt
	global_load_dword v119, v[176:177], off nt
	global_load_dword v120, v[178:179], off nt
	global_load_dword v121, v[180:181], off nt
	global_load_dword v122, v[182:183], off nt
	global_load_dword v123, v[184:185], off nt
	global_load_dword v124, v[186:187], off nt
	global_load_dword v125, v[188:189], off nt
	global_load_dword v126, v[190:191], off nt
	global_load_dword v127, v[192:193], off nt
	global_load_dword v128, v[64:65], off nt
	s_waitcnt vmcnt(62)
	ds_write2_b32 v24, v63, v66 offset1:66
	s_waitcnt vmcnt(60)
	ds_write2_b32 v24, v67, v68 offset0:132 offset1:198
	s_waitcnt vmcnt(58)
	ds_write2_b32 v27, v69, v70 offset0:8 offset1:74
	s_waitcnt vmcnt(56)
	ds_write2_b32 v27, v71, v72 offset0:140 offset1:206
	s_waitcnt vmcnt(54)
	ds_write2_b32 v28, v73, v74 offset0:16 offset1:82
	s_waitcnt vmcnt(52)
	ds_write2_b32 v28, v75, v76 offset0:148 offset1:214
	s_waitcnt vmcnt(50)
	ds_write2_b32 v29, v77, v78 offset0:24 offset1:90
	s_waitcnt vmcnt(48)
	ds_write2_b32 v29, v79, v80 offset0:156 offset1:222
	s_waitcnt vmcnt(46)
	ds_write2_b32 v30, v81, v82 offset0:32 offset1:98
	s_waitcnt vmcnt(44)
	ds_write2_b32 v30, v83, v84 offset0:164 offset1:230
	s_waitcnt vmcnt(42)
	ds_write2_b32 v31, v85, v86 offset0:40 offset1:106
	s_waitcnt vmcnt(40)
	ds_write2_b32 v31, v87, v88 offset0:172 offset1:238
	s_waitcnt vmcnt(38)
	ds_write2_b32 v32, v89, v90 offset0:48 offset1:114
	s_waitcnt vmcnt(36)
	ds_write2_b32 v32, v91, v92 offset0:180 offset1:246
	s_waitcnt vmcnt(34)
	ds_write2_b32 v33, v93, v94 offset0:56 offset1:122
	s_waitcnt vmcnt(32)
	ds_write2_b32 v33, v95, v96 offset0:188 offset1:254
	s_waitcnt vmcnt(30)
	ds_write2_b32 v34, v97, v98 offset0:64 offset1:130
	s_waitcnt vmcnt(28)
	ds_write2_b32 v35, v99, v100 offset0:68 offset1:134
	s_waitcnt vmcnt(26)
	ds_write2_b32 v36, v101, v102 offset0:72 offset1:138
	s_waitcnt vmcnt(24)
	ds_write2_b32 v37, v103, v104 offset0:76 offset1:142
	s_waitcnt vmcnt(22)
	ds_write2_b32 v38, v105, v106 offset0:80 offset1:146
	s_waitcnt vmcnt(20)
	ds_write2_b32 v39, v107, v108 offset0:84 offset1:150
	s_waitcnt vmcnt(18)
	ds_write2_b32 v40, v109, v110 offset0:88 offset1:154
	s_waitcnt vmcnt(16)
	ds_write2_b32 v41, v111, v112 offset0:92 offset1:158
	s_waitcnt vmcnt(14)
	ds_write2_b32 v42, v113, v114 offset0:96 offset1:162
	s_waitcnt vmcnt(12)
	ds_write2_b32 v43, v115, v116 offset0:100 offset1:166
	s_waitcnt vmcnt(10)
	ds_write2_b32 v44, v117, v118 offset0:104 offset1:170
	s_waitcnt vmcnt(8)
	ds_write2_b32 v45, v119, v120 offset0:108 offset1:174
	s_waitcnt vmcnt(6)
	ds_write2_b32 v46, v121, v122 offset0:112 offset1:178
	s_waitcnt vmcnt(4)
	ds_write2_b32 v47, v123, v124 offset0:116 offset1:182
	s_waitcnt vmcnt(2)
	ds_write2_b32 v48, v125, v126 offset0:120 offset1:186
	s_waitcnt vmcnt(0)
	ds_write2_b32 v49, v127, v128 offset0:124 offset1:190
	s_waitcnt lgkmcnt(0)
; #define LAS __attribute__((address_space(3)))
; template <int MODE>
; __device__ __forceinline__ void p0_transpose_item8(const float* W, int K, int N, unsigned char* WT, float scale, LAS float* scr, int item, int lane) {
;     ...
;     const int n = lane & 31, hf = lane >> 5;
;     const int r0 = (MODE == 0) ? n0 : (n0 / 128) * 256 + (n0 % 128) + (MODE == 2 ? 128 : 0);
; #pragma unroll
;     for (int p = 0; p < 4; ++p) { const int q = 2 * p + hf; const LAS float* s = scr + (16 * q) * 33 + n;
;         v4u o;
;         o.x = pg8::cvt4_fp8(s[0 * 33] * scale, s[1 * 33] * scale, s[2 * 33] * scale, s[3 * 33] * scale);
;         o.y = pg8::cvt4_fp8(s[4 * 33] * scale, s[5 * 33] * scale, s[6 * 33] * scale, s[7 * 33] * scale);
;         o.z = pg8::cvt4_fp8(s[8 * 33] * scale, s[9 * 33] * scale, s[10 * 33] * scale, s[11 * 33] * scale);
;         o.w = pg8::cvt4_fp8(s[12 * 33] * scale, s[13 * 33] * scale, s[14 * 33] * scale, s[15 * 33] * scale);
	s_bfe_u32 s18, s4, 0x70018
	s_add_i32 s18, s4, s18
	ds_read2_b32 v[66:67], v25 offset1:33
	ds_read2_b32 v[68:69], v25 offset0:66 offset1:99
	ds_read2_b32 v[70:71], v25 offset0:132 offset1:165
	ds_read2_b32 v[72:73], v25 offset0:198 offset1:231
	ds_read2_b32 v[74:75], v50 offset0:8 offset1:41
	ds_read2_b32 v[76:77], v50 offset0:140 offset1:173
	ds_read2_b32 v[78:79], v51 offset0:32 offset1:65
	ds_read2_b32 v[80:81], v51 offset0:164 offset1:197
	ds_read2_b32 v[82:83], v53 offset0:40 offset1:73
	ds_read2_b32 v[84:85], v53 offset0:172 offset1:205
	ds_read2_b32 v[86:87], v50 offset0:74 offset1:107
	ds_read2_b32 v[88:89], v50 offset0:206 offset1:239
	ds_read2_b32 v[90:91], v55 offset0:64 offset1:97
	ds_read2_b32 v[92:93], v55 offset0:196 offset1:229
	ds_read2_b32 v[94:95], v56 offset0:72 offset1:105
	ds_read2_b32 v[96:97], v56 offset0:204 offset1:237
	ds_read2_b32 v[98:99], v58 offset0:96 offset1:129
	ds_read2_b32 v[100:101], v59 offset0:100 offset1:133
	ds_read2_b32 v[102:103], v60 offset0:104 offset1:137
	ds_read2_b32 v[104:105], v61 offset0:108 offset1:141
	ds_read2_b32 v[106:107], v51 offset0:98 offset1:131
	ds_read2_b32 v[108:109], v52 offset0:102 offset1:135
	ds_read2_b32 v[110:111], v53 offset0:106 offset1:139
	ds_read2_b32 v[112:113], v54 offset0:110 offset1:143
	ds_read2_b32 v[114:115], v55 offset0:130 offset1:163
	ds_read2_b32 v[116:117], v56 offset0:6 offset1:39
	ds_read2_b32 v[118:119], v56 offset0:138 offset1:171
	ds_read2_b32 v[120:121], v57 offset0:14 offset1:47
	ds_read2_b32 v[122:123], v58 offset0:162 offset1:195
	ds_read2_b32 v[124:125], v60 offset0:38 offset1:71
	ds_read2_b32 v[126:127], v60 offset0:170 offset1:203
	ds_read2_b32 v[128:129], v62 offset0:46 offset1:79
	s_sext_i32_i16 s5, s5
	s_and_b32 s16, s18, 0xff80
	s_waitcnt lgkmcnt(14)
	v_mul_f32_e32 v63, 0x44000000, v66
	v_mul_f32_e32 v66, 0x44000000, v67
	v_mul_f32_e32 v67, 0x44000000, v68
	v_mul_f32_e32 v68, 0x44000000, v69
	v_mul_f32_e32 v69, 0x44000000, v70
	v_mul_f32_e32 v70, 0x44000000, v71
	v_mul_f32_e32 v71, 0x44000000, v72
	v_mul_f32_e32 v72, 0x44000000, v73
	v_mul_f32_e32 v73, 0x44000000, v74
	v_mul_f32_e32 v74, 0x44000000, v75
	v_mul_f32_e32 v75, 0x44000000, v76
	v_mul_f32_e32 v76, 0x44000000, v77
	v_mov_b32_e32 v2, 0
	v_mov_b32_e32 v3, 0
	v_mov_b32_e32 v4, 0
	v_mov_b32_e32 v5, 0
	s_lshl_b32 s5, s5, 6
	s_sub_i32 s4, s4, s16
	v_mul_f32_e32 v77, 0x44000000, v78
	v_mul_f32_e32 v78, 0x44000000, v79
	v_mul_f32_e32 v79, 0x44000000, v80
	v_mul_f32_e32 v80, 0x44000000, v81
	v_mul_f32_e32 v81, 0x44000000, v82
	v_mul_f32_e32 v82, 0x44000000, v83
	v_mul_f32_e32 v83, 0x44000000, v84
	v_mul_f32_e32 v84, 0x44000000, v85
	v_med3_f32 v63, v63, s9, v26
	v_med3_f32 v66, v66, s9, v26
	v_med3_f32 v69, v69, s9, v26
	v_med3_f32 v70, v70, s9, v26
	v_med3_f32 v73, v73, s9, v26
	v_med3_f32 v74, v74, s9, v26
	v_med3_f32 v75, v75, s9, v26
	v_med3_f32 v76, v76, s9, v26
	v_mov_b32_e32 v6, 0
	v_mov_b32_e32 v7, 0
	v_mov_b32_e32 v8, 0
	v_mov_b32_e32 v9, 0
	s_and_b32 s5, s5, 0xffffff00
	s_sext_i32_i16 s4, s4
	v_mul_f32_e32 v85, 0x44000000, v86
	v_mul_f32_e32 v86, 0x44000000, v87
	v_mul_f32_e32 v87, 0x44000000, v88
	v_mul_f32_e32 v88, 0x44000000, v89
	v_mul_f32_e32 v89, 0x44000000, v90
	v_mul_f32_e32 v90, 0x44000000, v91
	v_mul_f32_e32 v91, 0x44000000, v92
	v_mul_f32_e32 v92, 0x44000000, v93
	v_mul_f32_e32 v93, 0x44000000, v94
	v_mul_f32_e32 v94, 0x44000000, v95
	v_mul_f32_e32 v95, 0x44000000, v96
	v_mul_f32_e32 v96, 0x44000000, v97
	v_med3_f32 v77, v77, s9, v26
	v_med3_f32 v78, v78, s9, v26
	v_med3_f32 v79, v79, s9, v26
	v_med3_f32 v80, v80, s9, v26
	v_med3_f32 v81, v81, s9, v26
	v_med3_f32 v82, v82, s9, v26
	v_med3_f32 v83, v83, s9, v26
	v_med3_f32 v84, v84, s9, v26
	v_cvt_pk_fp8_f32 v2, v63, v66
	v_cvt_pk_fp8_f32 v3, v69, v70
	v_cvt_pk_fp8_f32 v4, v73, v74
	v_cvt_pk_fp8_f32 v5, v75, v76
	v_mov_b32_e32 v10, 0
	v_mov_b32_e32 v11, 0
	v_mov_b32_e32 v12, 0
	v_mov_b32_e32 v13, 0
	s_add_i32 s5, s5, s4
	v_mul_f32_e32 v97, 0x44000000, v98
	v_mul_f32_e32 v98, 0x44000000, v99
	v_mul_f32_e32 v99, 0x44000000, v100
	v_mul_f32_e32 v100, 0x44000000, v101
	s_waitcnt lgkmcnt(13)
	v_mul_f32_e32 v101, 0x44000000, v102
	v_mul_f32_e32 v102, 0x44000000, v103
	s_waitcnt lgkmcnt(12)
	v_mul_f32_e32 v103, 0x44000000, v104
	v_mul_f32_e32 v104, 0x44000000, v105
	v_med3_f32 v89, v89, s9, v26
	v_med3_f32 v90, v90, s9, v26
	v_med3_f32 v91, v91, s9, v26
	v_med3_f32 v92, v92, s9, v26
	v_med3_f32 v93, v93, s9, v26
	v_med3_f32 v94, v94, s9, v26
	v_med3_f32 v95, v95, s9, v26
	v_med3_f32 v96, v96, s9, v26
	v_cvt_pk_fp8_f32 v6, v77, v78
	v_cvt_pk_fp8_f32 v7, v79, v80
	v_cvt_pk_fp8_f32 v8, v81, v82
	v_cvt_pk_fp8_f32 v9, v83, v84
	v_mov_b32_e32 v14, 0
	v_mov_b32_e32 v15, 0
	v_mov_b32_e32 v16, 0
	v_mov_b32_e32 v17, 0
	v_or_b32_e32 v64, s5, v18
	v_med3_f32 v97, v97, s9, v26
	v_med3_f32 v98, v98, s9, v26
	v_med3_f32 v99, v99, s9, v26
	v_med3_f32 v100, v100, s9, v26
	v_med3_f32 v101, v101, s9, v26
	v_med3_f32 v102, v102, s9, v26
	v_med3_f32 v103, v103, s9, v26
	v_med3_f32 v104, v104, s9, v26
	v_cvt_pk_fp8_f32 v10, v89, v90
	v_cvt_pk_fp8_f32 v11, v91, v92
	v_cvt_pk_fp8_f32 v12, v93, v94
	v_cvt_pk_fp8_f32 v13, v95, v96
	v_ashrrev_i32_e32 v65, 31, v64
	s_waitcnt lgkmcnt(11)
; #define GAS __attribute__((address_space(1)))
; #define LAS __attribute__((address_space(3)))
; #define LDS_WAIT() asm volatile("s_waitcnt lgkmcnt(0)" ::: "memory")
; template <int MODE>
; __device__ __forceinline__ void p0_transpose_item8(const float* W, int K, int N, unsigned char* WT, float scale, LAS float* scr, int item, int lane) {
;     ...
;     for (int p = 0; p < 4; ++p) { const int q = 2 * p + hf; const LAS float* s = scr + (16 * q) * 33 + n;
;         v4u o;
;         o.x = pg8::cvt4_fp8(s[0 * 33] * scale, s[1 * 33] * scale, s[2 * 33] * scale, s[3 * 33] * scale);
;         o.y = pg8::cvt4_fp8(s[4 * 33] * scale, s[5 * 33] * scale, s[6 * 33] * scale, s[7 * 33] * scale);
;         o.z = pg8::cvt4_fp8(s[8 * 33] * scale, s[9 * 33] * scale, s[10 * 33] * scale, s[11 * 33] * scale);
;         o.w = pg8::cvt4_fp8(s[12 * 33] * scale, s[13 * 33] * scale, s[14 * 33] * scale, s[15 * 33] * scale);
;         *(GAS v4u*)(WT + (size_t)(r0 + n) * K + k0 + 16 * q) = o; }
;     LDS_WAIT(); asm volatile("" ::: "memory");
; template <int JOB>
; __device__ __forceinline__ void conv_job(Frame& F, const Args& A, int rank, int nw) {
;     ...
;     for (int it = rank; it < N; it += nw) {
;         if constexpr (JOB == JOB_W1A) p0_transpose_item8<1>(A.in[I_W1A], D, FF, ws + WS_W13A, S_W13, scr, it, F.lane);
;         if constexpr (JOB == JOB_W3A) p0_transpose_item8<2>(A.in[I_W3A], D, FF, ws + WS_W13A, S_W13, scr, it, F.lane);
	v_mul_f32_e32 v105, 0x44000000, v106
	v_mul_f32_e32 v106, 0x44000000, v107
	s_waitcnt lgkmcnt(10)
	v_mul_f32_e32 v107, 0x44000000, v108
	v_mul_f32_e32 v108, 0x44000000, v109
	s_waitcnt lgkmcnt(9)
	v_mul_f32_e32 v109, 0x44000000, v110
	v_mul_f32_e32 v110, 0x44000000, v111
	s_waitcnt lgkmcnt(8)
	v_mul_f32_e32 v111, 0x44000000, v112
	v_mul_f32_e32 v112, 0x44000000, v113
	v_med3_f32 v67, v67, s9, v26
	v_med3_f32 v68, v68, s9, v26
	v_med3_f32 v71, v71, s9, v26
	v_med3_f32 v72, v72, s9, v26
	v_med3_f32 v85, v85, s9, v26
	v_med3_f32 v86, v86, s9, v26
	v_med3_f32 v87, v87, s9, v26
	v_med3_f32 v88, v88, s9, v26
	v_cvt_pk_fp8_f32 v14, v97, v98
	v_cvt_pk_fp8_f32 v15, v99, v100
	v_cvt_pk_fp8_f32 v16, v101, v102
	v_cvt_pk_fp8_f32 v17, v103, v104
	v_lshlrev_b64 v[64:65], 12, v[64:65]
	s_waitcnt lgkmcnt(7)
	v_mul_f32_e32 v113, 0x44000000, v114
	v_mul_f32_e32 v114, 0x44000000, v115
	s_waitcnt lgkmcnt(6)
	v_mul_f32_e32 v115, 0x44000000, v116
	v_mul_f32_e32 v116, 0x44000000, v117
	s_waitcnt lgkmcnt(5)
	v_mul_f32_e32 v117, 0x44000000, v118
	v_mul_f32_e32 v118, 0x44000000, v119
	s_waitcnt lgkmcnt(4)
	v_mul_f32_e32 v119, 0x44000000, v120
	v_mul_f32_e32 v120, 0x44000000, v121
	v_med3_f32 v105, v105, s9, v26
	v_med3_f32 v106, v106, s9, v26
	v_med3_f32 v107, v107, s9, v26
	v_med3_f32 v108, v108, s9, v26
	v_med3_f32 v109, v109, s9, v26
	v_med3_f32 v110, v110, s9, v26
	v_med3_f32 v111, v111, s9, v26
	v_med3_f32 v112, v112, s9, v26
	v_cvt_pk_fp8_f32 v2, v67, v68 op_sel:[0,0,1]
	v_cvt_pk_fp8_f32 v3, v71, v72 op_sel:[0,0,1]
	v_cvt_pk_fp8_f32 v4, v85, v86 op_sel:[0,0,1]
	v_cvt_pk_fp8_f32 v5, v87, v88 op_sel:[0,0,1]
	s_ashr_i32 s3, s2, 31
	v_lshl_add_u64 v[64:65], s[10:11], 0, v[64:65]
	s_waitcnt lgkmcnt(3)
	v_mul_f32_e32 v121, 0x44000000, v122
	v_mul_f32_e32 v122, 0x44000000, v123
	s_waitcnt lgkmcnt(2)
	v_mul_f32_e32 v123, 0x44000000, v124
	v_mul_f32_e32 v124, 0x44000000, v125
	s_waitcnt lgkmcnt(1)
	v_mul_f32_e32 v125, 0x44000000, v126
	v_mul_f32_e32 v126, 0x44000000, v127
	s_waitcnt lgkmcnt(0)
	v_mul_f32_e32 v127, 0x44000000, v128
	v_mul_f32_e32 v128, 0x44000000, v129
	v_med3_f32 v113, v113, s9, v26
	v_med3_f32 v114, v114, s9, v26
	v_med3_f32 v115, v115, s9, v26
	v_med3_f32 v116, v116, s9, v26
	v_med3_f32 v117, v117, s9, v26
	v_med3_f32 v118, v118, s9, v26
	v_med3_f32 v119, v119, s9, v26
	v_med3_f32 v120, v120, s9, v26
	v_cvt_pk_fp8_f32 v6, v105, v106 op_sel:[0,0,1]
	v_cvt_pk_fp8_f32 v7, v107, v108 op_sel:[0,0,1]
	v_cvt_pk_fp8_f32 v8, v109, v110 op_sel:[0,0,1]
	v_cvt_pk_fp8_f32 v9, v111, v112 op_sel:[0,0,1]
	v_lshl_add_u64 v[64:65], v[64:65], 0, s[2:3]
	v_med3_f32 v121, v121, s9, v26
	v_med3_f32 v122, v122, s9, v26
	v_med3_f32 v123, v123, s9, v26
	v_med3_f32 v124, v124, s9, v26
	v_med3_f32 v125, v125, s9, v26
	v_med3_f32 v126, v126, s9, v26
	v_med3_f32 v127, v127, s9, v26
	v_med3_f32 v128, v128, s9, v26
	v_cvt_pk_fp8_f32 v10, v113, v114 op_sel:[0,0,1]
	v_cvt_pk_fp8_f32 v11, v115, v116 op_sel:[0,0,1]
	v_cvt_pk_fp8_f32 v12, v117, v118 op_sel:[0,0,1]
	v_cvt_pk_fp8_f32 v13, v119, v120 op_sel:[0,0,1]
	v_lshl_add_u64 v[64:65], v[64:65], 0, v[20:21]
	v_cvt_pk_fp8_f32 v14, v121, v122 op_sel:[0,0,1]
	v_cvt_pk_fp8_f32 v15, v123, v124 op_sel:[0,0,1]
	v_cvt_pk_fp8_f32 v16, v125, v126 op_sel:[0,0,1]
	v_cvt_pk_fp8_f32 v17, v127, v128 op_sel:[0,0,1]
	global_store_dwordx4 v[64:65], v[2:5], off
	global_store_dwordx4 v[64:65], v[6:9], off offset:32
	global_store_dwordx4 v[64:65], v[10:13], off offset:64
	global_store_dwordx4 v[64:65], v[14:17], off offset:96
	s_waitcnt lgkmcnt(0)
	s_add_i32 s15, s15, s1
	s_add_i32 s14, s14, s7
	s_cmpk_lt_i32 s15, 0x2b00
	s_cbranch_scc1 .LBB0_19
	s_sub_i32 s0, s1, s0
	s_add_i32 s0, s0, -1
	s_lshl_b32 s6, s0, 5
	v_readlane_b32 s68, v252, 3
	v_lshlrev_b32_e32 v2, 2, v18
	v_mov_b32_e32 v3, 0
	v_readlane_b32 s72, v252, 7
	v_readlane_b32 s73, v252, 8
	s_mov_b32 s8, 0xac00
	s_mov_b32 s9, 0xc3e00000
	v_lshl_add_u64 v[22:23], s[72:73], 0, v[2:3]
	v_mov_b32_e32 v26, 0x43e00000
	v_add_u32_e32 v27, 0x400, v24
	v_add_u32_e32 v28, 0x800, v24
	v_add_u32_e32 v29, 0xc00, v24
	v_add_u32_e32 v30, 0x1000, v24
	v_add_u32_e32 v31, 0x1400, v24
	v_add_u32_e32 v32, 0x1800, v24
	v_add_u32_e32 v33, 0x1c00, v24
	v_add_u32_e32 v34, 0x2000, v24
	v_add_u32_e32 v35, 0x2200, v24
	v_add_u32_e32 v36, 0x2400, v24
	v_add_u32_e32 v37, 0x2600, v24
	v_add_u32_e32 v38, 0x2800, v24
	v_add_u32_e32 v39, 0x2a00, v24
	v_add_u32_e32 v40, 0x2c00, v24
	v_add_u32_e32 v41, 0x2e00, v24
	v_add_u32_e32 v42, 0x3000, v24
	v_add_u32_e32 v43, 0x3200, v24
	v_add_u32_e32 v44, 0x3400, v24
	v_readlane_b32 s69, v252, 4
	v_readlane_b32 s70, v252, 5
	v_readlane_b32 s71, v252, 6
	v_readlane_b32 s74, v252, 9
	v_readlane_b32 s75, v252, 10
	v_readlane_b32 s76, v252, 11
	v_readlane_b32 s77, v252, 12
	v_readlane_b32 s78, v252, 13
	v_readlane_b32 s79, v252, 14
	v_readlane_b32 s80, v252, 15
	v_readlane_b32 s81, v252, 16
	v_readlane_b32 s82, v252, 17
	v_readlane_b32 s83, v252, 18

; #define GAS __attribute__((address_space(1)))
; #define LAS __attribute__((address_space(3)))
; template <int MODE>
; __device__ __forceinline__ void p0_transpose_item8(const float* W, int K, int N, unsigned char* WT, float scale, LAS float* scr, int item, int lane) {
;     const int nblk = N / 32, kb = item / nblk, nb = item % nblk, k0 = 128 * kb, n0 = 32 * nb;
;     const GAS float* Wg = (const GAS float*)W;
; #pragma unroll
;     for (int h2 = 0; h2 < 2; ++h2) { float ld[32];
; #pragma unroll
;         for (int i = 0; i < 32; ++i) { const int kk = 2 * (i + 32 * h2) + (lane >> 5); ld[i] = __builtin_nontemporal_load(&Wg[(size_t)(k0 + kk) * N + n0 + (lane & 31)]); }
; template <int JOB>
; __device__ __forceinline__ void conv_job(Frame& F, const Args& A, int rank, int nw) {
;     ...
;         if constexpr (JOB == JOB_W2B) p0_transpose_item8<0>(A.in[I_W2B], FF, D, ws + WS_W2B, S_W2, scr, it, F.lane);
.LBB0_771:
	s_ashr_i32 s2, s15, 31
	s_lshr_b32 s2, s2, 25
	s_add_i32 s2, s15, s2
	s_ashr_i32 s3, s2, 7
	s_and_b32 s2, s2, 0xffffff80
	s_lshl_b32 s4, s3, 12
	v_or_b32_e32 v64, s2, v19
	s_mul_i32 s5, s3, 0xfd500000
	s_sub_i32 s4, s14, s4
	v_or_b32_e32 v66, 2, v64
	v_or_b32_e32 v68, 4, v64
	v_or_b32_e32 v70, 6, v64
	v_or_b32_e32 v72, 8, v64
	v_or_b32_e32 v74, 10, v64
	v_or_b32_e32 v76, 12, v64
	v_or_b32_e32 v78, 14, v64
	v_or_b32_e32 v80, 16, v64
	v_or_b32_e32 v82, 18, v64
	v_or_b32_e32 v84, 20, v64
	v_or_b32_e32 v86, 22, v64
	v_or_b32_e32 v88, 24, v64
	v_or_b32_e32 v90, 26, v64
	v_or_b32_e32 v92, 28, v64
	v_or_b32_e32 v94, 30, v64
	v_or_b32_e32 v96, 32, v64
	v_or_b32_e32 v98, 34, v64
	v_or_b32_e32 v100, 36, v64
	v_or_b32_e32 v102, 38, v64
	v_or_b32_e32 v104, 40, v64
	v_or_b32_e32 v106, 42, v64
	v_or_b32_e32 v108, 44, v64
	v_or_b32_e32 v110, 46, v64
	v_or_b32_e32 v112, 48, v64
	v_or_b32_e32 v114, 50, v64
	v_or_b32_e32 v116, 52, v64
	v_or_b32_e32 v118, 54, v64
	v_or_b32_e32 v120, 56, v64
	v_or_b32_e32 v122, 58, v64
	v_or_b32_e32 v124, 60, v64
	v_or_b32_e32 v126, 62, v64
	v_or_b32_e32 v128, 64, v64
	v_ashrrev_i32_e32 v65, 31, v64
	v_or_b32_e32 v130, 0x42, v64
	v_or_b32_e32 v132, 0x44, v64
	v_or_b32_e32 v134, 0x46, v64
	v_or_b32_e32 v136, 0x48, v64
	v_or_b32_e32 v138, 0x4a, v64
	v_or_b32_e32 v140, 0x4c, v64
	v_or_b32_e32 v142, 0x4e, v64
	v_or_b32_e32 v144, 0x50, v64
	v_or_b32_e32 v146, 0x52, v64
	v_or_b32_e32 v148, 0x54, v64
	v_or_b32_e32 v150, 0x56, v64
	v_or_b32_e32 v152, 0x58, v64
	v_or_b32_e32 v154, 0x5a, v64
	v_or_b32_e32 v156, 0x5c, v64
	v_or_b32_e32 v158, 0x5e, v64
	v_or_b32_e32 v160, 0x60, v64
	v_or_b32_e32 v166, 0x62, v64
	v_or_b32_e32 v168, 0x64, v64
	v_or_b32_e32 v170, 0x66, v64
	v_or_b32_e32 v172, 0x68, v64
	v_or_b32_e32 v174, 0x6a, v64
	v_or_b32_e32 v176, 0x6c, v64
	v_or_b32_e32 v178, 0x6e, v64
	v_or_b32_e32 v180, 0x70, v64
	v_or_b32_e32 v182, 0x72, v64
	v_or_b32_e32 v184, 0x74, v64
	v_or_b32_e32 v186, 0x76, v64
	v_or_b32_e32 v188, 0x78, v64
	v_or_b32_e32 v190, 0x7a, v64
	v_or_b32_e32 v192, 0x7c, v64
	v_or_b32_e32 v194, 0x7e, v64
	v_add_u32_e32 v196, s5, v26
	s_ashr_i32 s5, s4, 31
	v_ashrrev_i32_e32 v67, 31, v66
	v_ashrrev_i32_e32 v69, 31, v68
	v_ashrrev_i32_e32 v71, 31, v70
	v_ashrrev_i32_e32 v73, 31, v72
	v_ashrrev_i32_e32 v75, 31, v74
	v_ashrrev_i32_e32 v77, 31, v76
	v_ashrrev_i32_e32 v79, 31, v78
	v_ashrrev_i32_e32 v81, 31, v80
	v_ashrrev_i32_e32 v83, 31, v82
	v_ashrrev_i32_e32 v85, 31, v84
	v_ashrrev_i32_e32 v87, 31, v86
	v_ashrrev_i32_e32 v89, 31, v88
	v_ashrrev_i32_e32 v91, 31, v90
	v_ashrrev_i32_e32 v93, 31, v92
	v_ashrrev_i32_e32 v95, 31, v94
	v_ashrrev_i32_e32 v97, 31, v96
	v_ashrrev_i32_e32 v99, 31, v98
	v_ashrrev_i32_e32 v101, 31, v100
	v_ashrrev_i32_e32 v103, 31, v102
	v_ashrrev_i32_e32 v105, 31, v104
	v_ashrrev_i32_e32 v107, 31, v106
	v_ashrrev_i32_e32 v109, 31, v108
	v_ashrrev_i32_e32 v111, 31, v110
	v_ashrrev_i32_e32 v113, 31, v112
	v_ashrrev_i32_e32 v115, 31, v114
	v_ashrrev_i32_e32 v117, 31, v116
	v_ashrrev_i32_e32 v119, 31, v118
	v_ashrrev_i32_e32 v121, 31, v120
	v_ashrrev_i32_e32 v123, 31, v122
	v_ashrrev_i32_e32 v125, 31, v124
	v_ashrrev_i32_e32 v127, 31, v126
	v_ashrrev_i32_e32 v129, 31, v128
	v_lshlrev_b64 v[64:65], 14, v[64:65]
	v_ashrrev_i32_e32 v131, 31, v130
	v_ashrrev_i32_e32 v133, 31, v132
	v_ashrrev_i32_e32 v135, 31, v134
	v_ashrrev_i32_e32 v137, 31, v136
	v_ashrrev_i32_e32 v139, 31, v138
	v_ashrrev_i32_e32 v141, 31, v140
	v_ashrrev_i32_e32 v143, 31, v142
	v_ashrrev_i32_e32 v145, 31, v144
	v_ashrrev_i32_e32 v147, 31, v146
	v_ashrrev_i32_e32 v149, 31, v148
	v_ashrrev_i32_e32 v151, 31, v150
	v_ashrrev_i32_e32 v153, 31, v152
	v_ashrrev_i32_e32 v155, 31, v154
	v_ashrrev_i32_e32 v157, 31, v156
	v_ashrrev_i32_e32 v159, 31, v158
	v_ashrrev_i32_e32 v161, 31, v160
	v_ashrrev_i32_e32 v167, 31, v166
	v_ashrrev_i32_e32 v169, 31, v168
	v_ashrrev_i32_e32 v171, 31, v170
	v_ashrrev_i32_e32 v173, 31, v172
	v_ashrrev_i32_e32 v175, 31, v174
	v_ashrrev_i32_e32 v177, 31, v176
	v_ashrrev_i32_e32 v179, 31, v178
	v_ashrrev_i32_e32 v181, 31, v180
	v_ashrrev_i32_e32 v183, 31, v182
	v_ashrrev_i32_e32 v185, 31, v184
	v_ashrrev_i32_e32 v187, 31, v186
	v_ashrrev_i32_e32 v189, 31, v188
	v_ashrrev_i32_e32 v191, 31, v190
	v_ashrrev_i32_e32 v193, 31, v192
	v_ashrrev_i32_e32 v195, 31, v194
	v_lshl_add_u64 v[198:199], s[4:5], 2, v[22:23]
	v_lshlrev_b64 v[66:67], 14, v[66:67]
	v_lshlrev_b64 v[68:69], 14, v[68:69]
	v_lshlrev_b64 v[70:71], 14, v[70:71]
	v_lshlrev_b64 v[72:73], 14, v[72:73]
	v_lshlrev_b64 v[74:75], 14, v[74:75]
	v_lshlrev_b64 v[76:77], 14, v[76:77]
	v_lshlrev_b64 v[78:79], 14, v[78:79]
	v_lshlrev_b64 v[80:81], 14, v[80:81]
	v_lshlrev_b64 v[82:83], 14, v[82:83]
	v_lshlrev_b64 v[84:85], 14, v[84:85]
	v_lshlrev_b64 v[86:87], 14, v[86:87]
	v_lshlrev_b64 v[88:89], 14, v[88:89]
	v_lshlrev_b64 v[90:91], 14, v[90:91]
	v_lshlrev_b64 v[92:93], 14, v[92:93]
	v_lshlrev_b64 v[94:95], 14, v[94:95]
	v_lshlrev_b64 v[96:97], 14, v[96:97]
	v_lshlrev_b64 v[98:99], 14, v[98:99]
	v_lshlrev_b64 v[100:101], 14, v[100:101]
	v_lshlrev_b64 v[102:103], 14, v[102:103]
	v_lshlrev_b64 v[104:105], 14, v[104:105]
	v_lshlrev_b64 v[106:107], 14, v[106:107]
	v_lshlrev_b64 v[108:109], 14, v[108:109]
	v_lshlrev_b64 v[110:111], 14, v[110:111]
	v_lshlrev_b64 v[112:113], 14, v[112:113]
	v_lshlrev_b64 v[114:115], 14, v[114:115]
	v_lshlrev_b64 v[116:117], 14, v[116:117]
	v_lshlrev_b64 v[118:119], 14, v[118:119]
	v_lshlrev_b64 v[120:121], 14, v[120:121]
	v_lshlrev_b64 v[122:123], 14, v[122:123]
	v_lshlrev_b64 v[124:125], 14, v[124:125]
	v_lshlrev_b64 v[126:127], 14, v[126:127]
	v_lshlrev_b64 v[128:129], 14, v[128:129]
	v_lshlrev_b64 v[130:131], 14, v[130:131]
; template <int MODE>
; __device__ __forceinline__ void p0_transpose_item8(const float* W, int K, int N, unsigned char* WT, float scale, LAS float* scr, int item, int lane) {
;     ...
;     for (int h2 = 0; h2 < 2; ++h2) { float ld[32];
; #pragma unroll
;         for (int i = 0; i < 32; ++i) { const int kk = 2 * (i + 32 * h2) + (lane >> 5); ld[i] = __builtin_nontemporal_load(&Wg[(size_t)(k0 + kk) * N + n0 + (lane & 31)]); }
	v_lshlrev_b64 v[132:133], 14, v[132:133]
	v_lshlrev_b64 v[134:135], 14, v[134:135]
	v_lshlrev_b64 v[136:137], 14, v[136:137]
	v_lshlrev_b64 v[138:139], 14, v[138:139]
	v_lshlrev_b64 v[140:141], 14, v[140:141]
	v_lshlrev_b64 v[142:143], 14, v[142:143]
	v_lshlrev_b64 v[144:145], 14, v[144:145]
	v_lshlrev_b64 v[146:147], 14, v[146:147]
	v_lshlrev_b64 v[148:149], 14, v[148:149]
	v_lshlrev_b64 v[150:151], 14, v[150:151]
	v_lshlrev_b64 v[152:153], 14, v[152:153]
	v_lshlrev_b64 v[154:155], 14, v[154:155]
	v_lshlrev_b64 v[156:157], 14, v[156:157]
	v_lshlrev_b64 v[158:159], 14, v[158:159]
	v_lshlrev_b64 v[160:161], 14, v[160:161]
	v_lshlrev_b64 v[166:167], 14, v[166:167]
	v_lshlrev_b64 v[168:169], 14, v[168:169]
	v_lshlrev_b64 v[170:171], 14, v[170:171]
	v_lshlrev_b64 v[172:173], 14, v[172:173]
	v_lshlrev_b64 v[174:175], 14, v[174:175]
	v_lshlrev_b64 v[176:177], 14, v[176:177]
	v_lshlrev_b64 v[178:179], 14, v[178:179]
	v_lshlrev_b64 v[180:181], 14, v[180:181]
	v_lshlrev_b64 v[182:183], 14, v[182:183]
	v_lshlrev_b64 v[184:185], 14, v[184:185]
	v_lshlrev_b64 v[186:187], 14, v[186:187]
	v_lshlrev_b64 v[188:189], 14, v[188:189]
	v_lshlrev_b64 v[190:191], 14, v[190:191]
	v_lshlrev_b64 v[192:193], 14, v[192:193]
	v_lshlrev_b64 v[194:195], 14, v[194:195]
	v_lshl_add_u64 v[64:65], v[198:199], 0, v[64:65]
	v_lshl_add_u64 v[66:67], v[198:199], 0, v[66:67]
	v_lshl_add_u64 v[68:69], v[198:199], 0, v[68:69]
	v_lshl_add_u64 v[70:71], v[198:199], 0, v[70:71]
	v_lshl_add_u64 v[72:73], v[198:199], 0, v[72:73]
	v_lshl_add_u64 v[74:75], v[198:199], 0, v[74:75]
	v_lshl_add_u64 v[76:77], v[198:199], 0, v[76:77]
	v_lshl_add_u64 v[78:79], v[198:199], 0, v[78:79]
	v_lshl_add_u64 v[80:81], v[198:199], 0, v[80:81]
	v_lshl_add_u64 v[82:83], v[198:199], 0, v[82:83]
	v_lshl_add_u64 v[84:85], v[198:199], 0, v[84:85]
	v_lshl_add_u64 v[86:87], v[198:199], 0, v[86:87]
	v_lshl_add_u64 v[88:89], v[198:199], 0, v[88:89]
	v_lshl_add_u64 v[90:91], v[198:199], 0, v[90:91]
	v_lshl_add_u64 v[92:93], v[198:199], 0, v[92:93]
	v_lshl_add_u64 v[94:95], v[198:199], 0, v[94:95]
	v_lshl_add_u64 v[96:97], v[198:199], 0, v[96:97]
	v_lshl_add_u64 v[98:99], v[198:199], 0, v[98:99]
	v_lshl_add_u64 v[100:101], v[198:199], 0, v[100:101]
	v_lshl_add_u64 v[102:103], v[198:199], 0, v[102:103]
	v_lshl_add_u64 v[104:105], v[198:199], 0, v[104:105]
	v_lshl_add_u64 v[106:107], v[198:199], 0, v[106:107]
	v_lshl_add_u64 v[108:109], v[198:199], 0, v[108:109]
	v_lshl_add_u64 v[110:111], v[198:199], 0, v[110:111]
	v_lshl_add_u64 v[112:113], v[198:199], 0, v[112:113]
	v_lshl_add_u64 v[114:115], v[198:199], 0, v[114:115]
	v_lshl_add_u64 v[116:117], v[198:199], 0, v[116:117]
	v_lshl_add_u64 v[118:119], v[198:199], 0, v[118:119]
	v_lshl_add_u64 v[120:121], v[198:199], 0, v[120:121]
	v_lshl_add_u64 v[122:123], v[198:199], 0, v[122:123]
	v_lshl_add_u64 v[124:125], v[198:199], 0, v[124:125]
	v_lshl_add_u64 v[126:127], v[198:199], 0, v[126:127]
	v_lshl_add_u64 v[128:129], v[198:199], 0, v[128:129]
	v_lshl_add_u64 v[130:131], v[198:199], 0, v[130:131]
	v_lshl_add_u64 v[132:133], v[198:199], 0, v[132:133]
	v_lshl_add_u64 v[134:135], v[198:199], 0, v[134:135]
	v_lshl_add_u64 v[136:137], v[198:199], 0, v[136:137]
	v_lshl_add_u64 v[138:139], v[198:199], 0, v[138:139]
	v_lshl_add_u64 v[140:141], v[198:199], 0, v[140:141]
	v_lshl_add_u64 v[142:143], v[198:199], 0, v[142:143]
	v_lshl_add_u64 v[144:145], v[198:199], 0, v[144:145]
	v_lshl_add_u64 v[146:147], v[198:199], 0, v[146:147]
	v_lshl_add_u64 v[148:149], v[198:199], 0, v[148:149]
	v_lshl_add_u64 v[150:151], v[198:199], 0, v[150:151]
	v_lshl_add_u64 v[152:153], v[198:199], 0, v[152:153]
	v_lshl_add_u64 v[154:155], v[198:199], 0, v[154:155]
	v_lshl_add_u64 v[156:157], v[198:199], 0, v[156:157]
	v_lshl_add_u64 v[158:159], v[198:199], 0, v[158:159]
	v_lshl_add_u64 v[160:161], v[198:199], 0, v[160:161]
	v_lshl_add_u64 v[166:167], v[198:199], 0, v[166:167]
	v_lshl_add_u64 v[168:169], v[198:199], 0, v[168:169]
	v_lshl_add_u64 v[170:171], v[198:199], 0, v[170:171]
	v_lshl_add_u64 v[172:173], v[198:199], 0, v[172:173]
	v_lshl_add_u64 v[174:175], v[198:199], 0, v[174:175]
	v_lshl_add_u64 v[176:177], v[198:199], 0, v[176:177]
	v_lshl_add_u64 v[178:179], v[198:199], 0, v[178:179]
	v_lshl_add_u64 v[180:181], v[198:199], 0, v[180:181]
	v_lshl_add_u64 v[182:183], v[198:199], 0, v[182:183]
	v_lshl_add_u64 v[184:185], v[198:199], 0, v[184:185]
	v_lshl_add_u64 v[186:187], v[198:199], 0, v[186:187]
	v_lshl_add_u64 v[188:189], v[198:199], 0, v[188:189]
	v_lshl_add_u64 v[190:191], v[198:199], 0, v[190:191]
	v_lshl_add_u64 v[192:193], v[198:199], 0, v[192:193]
	v_lshl_add_u64 v[194:195], v[198:199], 0, v[194:195]
	global_load_dword v163, v[64:65], off nt
	s_nop 0
	global_load_dword v66, v[66:67], off nt
	s_nop 0
	global_load_dword v67, v[68:69], off nt
	s_nop 0
	global_load_dword v68, v[70:71], off nt
	global_load_dword v69, v[72:73], off nt
	s_nop 0
	global_load_dword v70, v[74:75], off nt
	global_load_dword v71, v[76:77], off nt
	global_load_dword v72, v[78:79], off nt
	global_load_dword v73, v[80:81], off nt
	s_nop 0
	global_load_dword v74, v[82:83], off nt
	global_load_dword v75, v[84:85], off nt
	global_load_dword v76, v[86:87], off nt
	global_load_dword v77, v[88:89], off nt
	global_load_dword v78, v[90:91], off nt
	global_load_dword v79, v[92:93], off nt
	global_load_dword v80, v[94:95], off nt
	global_load_dword v81, v[96:97], off nt
	global_load_dword v82, v[98:99], off nt
	global_load_dword v83, v[100:101], off nt
	global_load_dword v84, v[102:103], off nt
	global_load_dword v85, v[104:105], off nt
	global_load_dword v86, v[106:107], off nt
	global_load_dword v87, v[108:109], off nt
; #define LAS __attribute__((address_space(3)))
; #define LDS_WAIT() asm volatile("s_waitcnt lgkmcnt(0)" ::: "memory")
; template <int MODE>
; __device__ __forceinline__ void p0_transpose_item8(const float* W, int K, int N, unsigned char* WT, float scale, LAS float* scr, int item, int lane) {
;     ...
;         for (int i = 0; i < 32; ++i) { const int kk = 2 * (i + 32 * h2) + (lane >> 5); ld[i] = __builtin_nontemporal_load(&Wg[(size_t)(k0 + kk) * N + n0 + (lane & 31)]); }
; #pragma unroll
;         for (int i = 0; i < 32; ++i) { const int kk = 2 * (i + 32 * h2) + (lane >> 5); scr[kk * 33 + (lane & 31)] = ld[i]; } }
;     LDS_WAIT(); asm volatile("" ::: "memory");
;     const int n = lane & 31, hf = lane >> 5;
;     const int r0 = (MODE == 0) ? n0 : (n0 / 128) * 256 + (n0 % 128) + (MODE == 2 ? 128 : 0);
; #pragma unroll
;     for (int p = 0; p < 4; ++p) { const int q = 2 * p + hf; const LAS float* s = scr + (16 * q) * 33 + n;
;         v4u o;
;         o.x = pg8::cvt4_fp8(s[0 * 33] * scale, s[1 * 33] * scale, s[2 * 33] * scale, s[3 * 33] * scale);
;         o.y = pg8::cvt4_fp8(s[4 * 33] * scale, s[5 * 33] * scale, s[6 * 33] * scale, s[7 * 33] * scale);
;         o.z = pg8::cvt4_fp8(s[8 * 33] * scale, s[9 * 33] * scale, s[10 * 33] * scale, s[11 * 33] * scale);
;         o.w = pg8::cvt4_fp8(s[12 * 33] * scale, s[13 * 33] * scale, s[14 * 33] * scale, s[15 * 33] * scale);
	global_load_dword v88, v[110:111], off nt
	global_load_dword v89, v[112:113], off nt
	global_load_dword v90, v[114:115], off nt
	global_load_dword v91, v[116:117], off nt
	global_load_dword v92, v[118:119], off nt
	global_load_dword v93, v[120:121], off nt
	global_load_dword v94, v[122:123], off nt
	global_load_dword v95, v[124:125], off nt
	global_load_dword v96, v[126:127], off nt
	global_load_dword v97, v[128:129], off nt
	global_load_dword v98, v[130:131], off nt
	global_load_dword v99, v[132:133], off nt
	global_load_dword v100, v[134:135], off nt
	global_load_dword v101, v[136:137], off nt
	global_load_dword v102, v[138:139], off nt
	global_load_dword v103, v[140:141], off nt
	global_load_dword v104, v[142:143], off nt
	global_load_dword v105, v[144:145], off nt
	global_load_dword v106, v[146:147], off nt
	global_load_dword v107, v[148:149], off nt
	global_load_dword v108, v[150:151], off nt
	global_load_dword v109, v[152:153], off nt
	global_load_dword v110, v[154:155], off nt
	global_load_dword v111, v[156:157], off nt
	global_load_dword v112, v[158:159], off nt
	global_load_dword v113, v[160:161], off nt
	global_load_dword v114, v[166:167], off nt
	global_load_dword v115, v[168:169], off nt
	global_load_dword v116, v[170:171], off nt
	global_load_dword v117, v[172:173], off nt
	global_load_dword v118, v[174:175], off nt
	global_load_dword v119, v[176:177], off nt
	global_load_dword v120, v[178:179], off nt
	global_load_dword v121, v[180:181], off nt
	global_load_dword v122, v[182:183], off nt
	global_load_dword v123, v[184:185], off nt
	global_load_dword v124, v[186:187], off nt
	global_load_dword v125, v[188:189], off nt
	global_load_dword v126, v[190:191], off nt
	global_load_dword v127, v[192:193], off nt
	global_load_dword v128, v[194:195], off nt
	s_waitcnt vmcnt(0)
	ds_write2_b32 v24, v163, v66 offset1:66
	ds_write2_b32 v24, v67, v68 offset0:132 offset1:198
	ds_write2_b32 v28, v69, v70 offset0:8 offset1:74
	ds_write2_b32 v28, v71, v72 offset0:140 offset1:206
	ds_write2_b32 v29, v73, v74 offset0:16 offset1:82
	ds_write2_b32 v29, v75, v76 offset0:148 offset1:214
	ds_write2_b32 v30, v77, v78 offset0:24 offset1:90
	ds_write2_b32 v30, v79, v80 offset0:156 offset1:222
	ds_write2_b32 v31, v81, v82 offset0:32 offset1:98
	ds_write2_b32 v31, v83, v84 offset0:164 offset1:230
	ds_write2_b32 v32, v85, v86 offset0:40 offset1:106
	ds_write2_b32 v32, v87, v88 offset0:172 offset1:238
	ds_write2_b32 v33, v89, v90 offset0:48 offset1:114
	ds_write2_b32 v33, v91, v92 offset0:180 offset1:246
	ds_write2_b32 v34, v93, v94 offset0:56 offset1:122
	ds_write2_b32 v34, v95, v96 offset0:188 offset1:254
	ds_write2_b32 v35, v97, v98 offset0:64 offset1:130
	ds_write2_b32 v36, v99, v100 offset0:68 offset1:134
	ds_write2_b32 v37, v101, v102 offset0:72 offset1:138
	ds_write2_b32 v38, v103, v104 offset0:76 offset1:142
	ds_write2_b32 v39, v105, v106 offset0:80 offset1:146
	ds_write2_b32 v40, v107, v108 offset0:84 offset1:150
	ds_write2_b32 v41, v109, v110 offset0:88 offset1:154
	ds_write2_b32 v42, v111, v112 offset0:92 offset1:158
	ds_write2_b32 v43, v113, v114 offset0:96 offset1:162
	ds_write2_b32 v44, v115, v116 offset0:100 offset1:166
	ds_write2_b32 v45, v117, v118 offset0:104 offset1:170
	ds_write2_b32 v46, v119, v120 offset0:108 offset1:174
	ds_write2_b32 v47, v121, v122 offset0:112 offset1:178
	ds_write2_b32 v48, v123, v124 offset0:116 offset1:182
	ds_write2_b32 v49, v125, v126 offset0:120 offset1:186
	ds_write2_b32 v50, v127, v128 offset0:124 offset1:190
	s_waitcnt lgkmcnt(0)
	ds_read2_b32 v[66:67], v25 offset1:33
	ds_read2_b32 v[68:69], v25 offset0:66 offset1:99
	ds_read2_b32 v[70:71], v25 offset0:132 offset1:165
	ds_read2_b32 v[72:73], v25 offset0:198 offset1:231
	ds_read2_b32 v[74:75], v51 offset0:8 offset1:41
	ds_read2_b32 v[76:77], v51 offset0:74 offset1:107
	ds_read2_b32 v[78:79], v51 offset0:140 offset1:173
	ds_read2_b32 v[80:81], v51 offset0:206 offset1:239
	ds_read2_b32 v[82:83], v52 offset0:32 offset1:65
	ds_read2_b32 v[84:85], v52 offset0:98 offset1:131
	ds_read2_b32 v[86:87], v52 offset0:164 offset1:197
	ds_read2_b32 v[88:89], v53 offset0:102 offset1:135
	ds_read2_b32 v[90:91], v54 offset0:40 offset1:73
	ds_read2_b32 v[92:93], v54 offset0:106 offset1:139
	ds_read2_b32 v[94:95], v54 offset0:172 offset1:205
	ds_read2_b32 v[96:97], v55 offset0:110 offset1:143
	ds_read2_b32 v[98:99], v56 offset0:64 offset1:97
	ds_read2_b32 v[100:101], v56 offset0:130 offset1:163
	ds_read2_b32 v[102:103], v56 offset0:196 offset1:229
	ds_read2_b32 v[104:105], v57 offset0:6 offset1:39
	ds_read2_b32 v[106:107], v57 offset0:72 offset1:105
	ds_read2_b32 v[108:109], v57 offset0:138 offset1:171
	ds_read2_b32 v[110:111], v57 offset0:204 offset1:237
	ds_read2_b32 v[112:113], v58 offset0:14 offset1:47
	ds_read2_b32 v[114:115], v59 offset0:96 offset1:129
	ds_read2_b32 v[116:117], v59 offset0:162 offset1:195
	ds_read2_b32 v[118:119], v60 offset0:100 offset1:133
	ds_read2_b32 v[120:121], v61 offset0:38 offset1:71
	ds_read2_b32 v[122:123], v61 offset0:104 offset1:137
	ds_read2_b32 v[124:125], v61 offset0:170 offset1:203
	ds_read2_b32 v[126:127], v62 offset0:108 offset1:141
	ds_read2_b32 v[128:129], v63 offset0:46 offset1:79
	s_waitcnt lgkmcnt(14)
; #define GAS __attribute__((address_space(1)))
; #define LAS __attribute__((address_space(3)))
; #define LDS_WAIT() asm volatile("s_waitcnt lgkmcnt(0)" ::: "memory")
; template <int MODE>
; __device__ __forceinline__ void p0_transpose_item8(const float* W, int K, int N, unsigned char* WT, float scale, LAS float* scr, int item, int lane) {
;     ...
;     for (int p = 0; p < 4; ++p) { const int q = 2 * p + hf; const LAS float* s = scr + (16 * q) * 33 + n;
;         v4u o;
;         o.x = pg8::cvt4_fp8(s[0 * 33] * scale, s[1 * 33] * scale, s[2 * 33] * scale, s[3 * 33] * scale);
;         o.y = pg8::cvt4_fp8(s[4 * 33] * scale, s[5 * 33] * scale, s[6 * 33] * scale, s[7 * 33] * scale);
;         o.z = pg8::cvt4_fp8(s[8 * 33] * scale, s[9 * 33] * scale, s[10 * 33] * scale, s[11 * 33] * scale);
;         o.w = pg8::cvt4_fp8(s[12 * 33] * scale, s[13 * 33] * scale, s[14 * 33] * scale, s[15 * 33] * scale);
;         *(GAS v4u*)(WT + (size_t)(r0 + n) * K + k0 + 16 * q) = o; }
;     LDS_WAIT(); asm volatile("" ::: "memory");
	v_mul_f32_e32 v66, 0x44000000, v66
	v_mul_f32_e32 v67, 0x44000000, v67
	v_mul_f32_e32 v70, 0x44000000, v70
	v_mul_f32_e32 v71, 0x44000000, v71
	v_mul_f32_e32 v74, 0x44000000, v74
	v_mul_f32_e32 v75, 0x44000000, v75
	v_mul_f32_e32 v78, 0x44000000, v78
	v_mul_f32_e32 v79, 0x44000000, v79
	v_mov_b32_e32 v2, 0
	v_mov_b32_e32 v3, 0
	v_mov_b32_e32 v4, 0
	v_mov_b32_e32 v5, 0
	v_mul_f32_e32 v82, 0x44000000, v82
	v_mul_f32_e32 v83, 0x44000000, v83
	v_mul_f32_e32 v86, 0x44000000, v86
	v_mul_f32_e32 v87, 0x44000000, v87
	v_mul_f32_e32 v90, 0x44000000, v90
	v_mul_f32_e32 v91, 0x44000000, v91
	v_mul_f32_e32 v94, 0x44000000, v94
	v_mul_f32_e32 v95, 0x44000000, v95
	v_med3_f32 v66, v66, s11, v27
	v_med3_f32 v67, v67, s11, v27
	v_med3_f32 v70, v70, s11, v27
	v_med3_f32 v71, v71, s11, v27
	v_med3_f32 v74, v74, s11, v27
	v_med3_f32 v75, v75, s11, v27
	v_med3_f32 v78, v78, s11, v27
	v_med3_f32 v79, v79, s11, v27
	v_mov_b32_e32 v6, 0
	v_mov_b32_e32 v7, 0
	v_mov_b32_e32 v8, 0
	v_mov_b32_e32 v9, 0
	v_mul_f32_e32 v98, 0x44000000, v98
	v_mul_f32_e32 v99, 0x44000000, v99
	s_waitcnt lgkmcnt(13)
	v_mul_f32_e32 v102, 0x44000000, v102
	v_mul_f32_e32 v103, 0x44000000, v103
	s_waitcnt lgkmcnt(11)
	v_mul_f32_e32 v106, 0x44000000, v106
	v_mul_f32_e32 v107, 0x44000000, v107
	s_waitcnt lgkmcnt(9)
	v_mul_f32_e32 v110, 0x44000000, v110
	v_mul_f32_e32 v111, 0x44000000, v111
	v_med3_f32 v82, v82, s11, v27
	v_med3_f32 v83, v83, s11, v27
	v_med3_f32 v86, v86, s11, v27
	v_med3_f32 v87, v87, s11, v27
	v_med3_f32 v90, v90, s11, v27
	v_med3_f32 v91, v91, s11, v27
	v_med3_f32 v94, v94, s11, v27
	v_med3_f32 v95, v95, s11, v27
	v_cvt_pk_fp8_f32 v2, v66, v67
	v_cvt_pk_fp8_f32 v3, v70, v71
	v_cvt_pk_fp8_f32 v4, v74, v75
	v_cvt_pk_fp8_f32 v5, v78, v79
	v_mov_b32_e32 v10, 0
	v_mov_b32_e32 v11, 0
	v_mov_b32_e32 v12, 0
	v_mov_b32_e32 v13, 0
	s_waitcnt lgkmcnt(7)
	v_mul_f32_e32 v114, 0x44000000, v114
	v_mul_f32_e32 v115, 0x44000000, v115
	s_waitcnt lgkmcnt(5)
	v_mul_f32_e32 v118, 0x44000000, v118
	v_mul_f32_e32 v119, 0x44000000, v119
	s_waitcnt lgkmcnt(3)
	v_mul_f32_e32 v122, 0x44000000, v122
	v_mul_f32_e32 v123, 0x44000000, v123
	s_waitcnt lgkmcnt(1)
	v_mul_f32_e32 v126, 0x44000000, v126
	v_mul_f32_e32 v127, 0x44000000, v127
	v_med3_f32 v98, v98, s11, v27
	v_med3_f32 v99, v99, s11, v27
	v_med3_f32 v102, v102, s11, v27
	v_med3_f32 v103, v103, s11, v27
	v_med3_f32 v106, v106, s11, v27
	v_med3_f32 v107, v107, s11, v27
	v_med3_f32 v110, v110, s11, v27
	v_med3_f32 v111, v111, s11, v27
	v_cvt_pk_fp8_f32 v6, v82, v83
	v_cvt_pk_fp8_f32 v7, v86, v87
	v_cvt_pk_fp8_f32 v8, v90, v91
	v_cvt_pk_fp8_f32 v9, v94, v95
	v_mov_b32_e32 v14, 0
	v_mov_b32_e32 v15, 0
	v_mov_b32_e32 v16, 0
	v_mov_b32_e32 v17, 0
	v_mul_f32_e32 v68, 0x44000000, v68
	v_mul_f32_e32 v69, 0x44000000, v69
	v_mul_f32_e32 v72, 0x44000000, v72
	v_mul_f32_e32 v73, 0x44000000, v73
	v_mul_f32_e32 v76, 0x44000000, v76
	v_mul_f32_e32 v77, 0x44000000, v77
	v_mul_f32_e32 v80, 0x44000000, v80
	v_mul_f32_e32 v81, 0x44000000, v81
	v_med3_f32 v114, v114, s11, v27
	v_med3_f32 v115, v115, s11, v27
	v_med3_f32 v118, v118, s11, v27
	v_med3_f32 v119, v119, s11, v27
	v_med3_f32 v122, v122, s11, v27
	v_med3_f32 v123, v123, s11, v27
	v_med3_f32 v126, v126, s11, v27
	v_med3_f32 v127, v127, s11, v27
	v_cvt_pk_fp8_f32 v10, v98, v99
	v_cvt_pk_fp8_f32 v11, v102, v103
	v_cvt_pk_fp8_f32 v12, v106, v107
	v_cvt_pk_fp8_f32 v13, v110, v111
	v_mul_f32_e32 v84, 0x44000000, v84
	v_mul_f32_e32 v85, 0x44000000, v85
	v_mul_f32_e32 v88, 0x44000000, v88
	v_mul_f32_e32 v89, 0x44000000, v89
	v_mul_f32_e32 v92, 0x44000000, v92
	v_mul_f32_e32 v93, 0x44000000, v93
	v_mul_f32_e32 v96, 0x44000000, v96
	v_mul_f32_e32 v97, 0x44000000, v97
	v_med3_f32 v68, v68, s11, v27
	v_med3_f32 v69, v69, s11, v27
	v_med3_f32 v72, v72, s11, v27
	v_med3_f32 v73, v73, s11, v27
	v_med3_f32 v76, v76, s11, v27
	v_med3_f32 v77, v77, s11, v27
	v_med3_f32 v80, v80, s11, v27
	v_med3_f32 v81, v81, s11, v27
	v_cvt_pk_fp8_f32 v14, v114, v115
	v_cvt_pk_fp8_f32 v15, v118, v119
	v_cvt_pk_fp8_f32 v16, v122, v123
	v_cvt_pk_fp8_f32 v17, v126, v127
	v_ashrrev_i32_e32 v197, 31, v196
	v_mul_f32_e32 v100, 0x44000000, v100
	v_mul_f32_e32 v101, 0x44000000, v101
	v_mul_f32_e32 v104, 0x44000000, v104
	v_mul_f32_e32 v105, 0x44000000, v105
	v_mul_f32_e32 v108, 0x44000000, v108
	v_mul_f32_e32 v109, 0x44000000, v109
	v_mul_f32_e32 v112, 0x44000000, v112
	v_mul_f32_e32 v113, 0x44000000, v113
	v_med3_f32 v84, v84, s11, v27
	v_med3_f32 v85, v85, s11, v27
	v_med3_f32 v88, v88, s11, v27
	v_med3_f32 v89, v89, s11, v27
	v_med3_f32 v92, v92, s11, v27
	v_med3_f32 v93, v93, s11, v27
	v_med3_f32 v96, v96, s11, v27
	v_med3_f32 v97, v97, s11, v27
	v_cvt_pk_fp8_f32 v2, v68, v69 op_sel:[0,0,1]
	v_cvt_pk_fp8_f32 v3, v72, v73 op_sel:[0,0,1]
	v_cvt_pk_fp8_f32 v4, v76, v77 op_sel:[0,0,1]
	v_cvt_pk_fp8_f32 v5, v80, v81 op_sel:[0,0,1]
	s_ashr_i32 s3, s2, 31
	v_lshl_add_u64 v[196:197], s[12:13], 0, v[196:197]
	v_mul_f32_e32 v116, 0x44000000, v116
	v_mul_f32_e32 v117, 0x44000000, v117
	v_mul_f32_e32 v120, 0x44000000, v120
	v_mul_f32_e32 v121, 0x44000000, v121
	v_mul_f32_e32 v124, 0x44000000, v124
	v_mul_f32_e32 v125, 0x44000000, v125
	s_waitcnt lgkmcnt(0)
	v_mul_f32_e32 v128, 0x44000000, v128
	v_mul_f32_e32 v129, 0x44000000, v129
	v_med3_f32 v100, v100, s11, v27
	v_med3_f32 v101, v101, s11, v27
	v_med3_f32 v104, v104, s11, v27
	v_med3_f32 v105, v105, s11, v27
	v_med3_f32 v108, v108, s11, v27
	v_med3_f32 v109, v109, s11, v27
	v_med3_f32 v112, v112, s11, v27
	v_med3_f32 v113, v113, s11, v27
	v_cvt_pk_fp8_f32 v6, v84, v85 op_sel:[0,0,1]
	v_cvt_pk_fp8_f32 v7, v88, v89 op_sel:[0,0,1]
	v_cvt_pk_fp8_f32 v8, v92, v93 op_sel:[0,0,1]
	v_cvt_pk_fp8_f32 v9, v96, v97 op_sel:[0,0,1]
	v_lshl_add_u64 v[196:197], v[196:197], 0, s[2:3]
	v_med3_f32 v116, v116, s11, v27
	v_med3_f32 v117, v117, s11, v27
	v_med3_f32 v120, v120, s11, v27
	v_med3_f32 v121, v121, s11, v27
	v_med3_f32 v124, v124, s11, v27
	v_med3_f32 v125, v125, s11, v27
	v_med3_f32 v128, v128, s11, v27
	v_med3_f32 v129, v129, s11, v27
	v_cvt_pk_fp8_f32 v10, v100, v101 op_sel:[0,0,1]
	v_cvt_pk_fp8_f32 v11, v104, v105 op_sel:[0,0,1]
	v_cvt_pk_fp8_f32 v12, v108, v109 op_sel:[0,0,1]
	v_cvt_pk_fp8_f32 v13, v112, v113 op_sel:[0,0,1]
	v_lshl_add_u64 v[64:65], v[196:197], 0, v[20:21]
	v_cvt_pk_fp8_f32 v14, v116, v117 op_sel:[0,0,1]
	v_cvt_pk_fp8_f32 v15, v120, v121 op_sel:[0,0,1]
	v_cvt_pk_fp8_f32 v16, v124, v125 op_sel:[0,0,1]
	v_cvt_pk_fp8_f32 v17, v128, v129 op_sel:[0,0,1]
	global_store_dwordx4 v[64:65], v[2:5], off
	global_store_dwordx4 v[64:65], v[6:9], off offset:32
	global_store_dwordx4 v[64:65], v[10:13], off offset:64
	global_store_dwordx4 v[64:65], v[14:17], off offset:96
	s_waitcnt lgkmcnt(0)
	s_add_i32 s15, s15, s1
	s_add_i32 s14, s14, s9
	s_cmpk_lt_i32 s15, 0x2b00
	v_add_u32_e32 v26, s10, v26
	s_cbranch_scc1 .LBB0_771
; #define SEAM(k) do { if (IN(k) && IN((k) + 1)) xcd_barrier(bar); } while (0)
; template <int JOB>
; __device__ __forceinline__ void conv_job(Frame& F, const Args& A, int rank, int nw) {
;     ...
;     for (int it = rank; it < N; it += nw) {
; __global__ void __launch_bounds__(NWAVES * 64, 2) mk_fwd(Args args) {
;     ...
;             if (cb >= left) { const int rank = (cb - left) * NWAVES + F.wave, nw = (F.G - left) * NWAVES; conv_job<JOB_W2B>(F, args, rank, nw); conv_job<JOB_W1B>(F, args, rank, nw); } } } SEAM(8);
	s_sub_i32 s0, s1, s0
	s_add_i32 s0, s0, -1
	s_lshl_b32 s8, s0, 5
	v_readlane_b32 s72, v252, 19
	v_lshlrev_b32_e32 v2, 2, v18
	v_mov_b32_e32 v3, 0
	v_readlane_b32 s76, v252, 23
	v_readlane_b32 s77, v252, 24
	s_mov_b32 s10, 0xac00
	s_mov_b32 s11, 0xc3e00000
	v_lshl_add_u64 v[22:23], s[76:77], 0, v[2:3]
	v_mov_b32_e32 v26, 0x43e00000
	v_readlane_b32 s73, v252, 20
	v_readlane_b32 s74, v252, 21
	v_readlane_b32 s75, v252, 22
	v_readlane_b32 s78, v252, 25
	v_readlane_b32 s79, v252, 26
	v_readlane_b32 s80, v252, 27
	v_readlane_b32 s81, v252, 28
	v_readlane_b32 s82, v252, 29
	v_readlane_b32 s83, v252, 30
	v_readlane_b32 s84, v252, 31
	v_readlane_b32 s85, v252, 32
	v_readlane_b32 s86, v252, 33
	v_readlane_b32 s87, v252, 34
